# grid barrier: the acquire's L1 invalidate is issued on arrival (with the L2 write-back on the XCD leader) instead of after the release; plus 132 mem workgroups in the mixer
# speedup vs baseline: 1.0186x; 1.0157x over previous
.LBB0_529:
	s_or_b64 exec, exec, s[10:11]
	v_cvt_f32_u32_e32 v4, v2
	s_waitcnt vmcnt(0)
	v_readfirstlane_b32 s0, v3
	v_sub_u32_e32 v3, 0, v2
	v_rcp_iflag_f32_e32 v4, v4
	v_add_u32_e32 v5, s0, v1
	v_mul_f32_e32 v4, 0x4f7ffffe, v4
	v_cvt_u32_f32_e32 v4, v4
	v_mul_lo_u32 v1, v3, v4
	v_mul_hi_u32 v1, v4, v1
	v_add_u32_e32 v1, v4, v1
	v_mul_hi_u32 v1, v5, v1
	v_mul_lo_u32 v3, v1, v2
	v_sub_u32_e32 v3, v5, v3
	v_add_u32_e32 v4, 1, v1
	v_cmp_ge_u32_e32 vcc, v3, v2
	s_nop 1
	v_cndmask_b32_e32 v1, v1, v4, vcc
	v_sub_u32_e32 v4, v3, v2
	v_cndmask_b32_e32 v3, v3, v4, vcc
	v_add_u32_e32 v4, 1, v1
	v_cmp_ge_u32_e32 vcc, v3, v2
	v_add_u32_e32 v3, 1, v5
	s_nop 0
	v_cndmask_b32_e32 v1, v1, v4, vcc
	v_mul_lo_u32 v4, v2, v1
	v_add_u32_e32 v2, v4, v2
	v_cmp_ne_u32_e32 vcc, v3, v2
	s_and_saveexec_b64 s[0:1], vcc
	s_xor_b64 s[8:9], exec, s[0:1]
	s_cbranch_execz .LBB0_543
	buffer_inv sc1
	s_waitcnt lgkmcnt(0)
	v_mov_b32_e32 v0, 0x2000
	global_load_dword v0, v0, s[6:7] offset:1024 sc1
	s_add_u32 s14, s6, 0x2400
	s_addc_u32 s15, s7, 0
	s_waitcnt vmcnt(0)
	v_cmp_eq_u32_e32 vcc, v0, v1
	s_and_saveexec_b64 s[10:11], vcc
	s_cbranch_execz .LBB0_542
	v_readlane_b32 s0, v255, 4
	v_readlane_b32 s1, v255, 5
	s_add_u32 s12, s0, 0x4200
	s_addc_u32 s13, s1, 0
	s_mov_b32 s0, 1
	s_mov_b64 s[16:17], 0
	v_mov_b32_e32 v0, 0
	s_branch .LBB0_533

.LBB0_542:
	s_or_b64 exec, exec, s[10:11]
	s_waitcnt vmcnt(0)
	s_waitcnt vmcnt(0)
.LBB0_543:
	s_andn2_saveexec_b64 s[0:1], s[8:9]
	s_cbranch_execz .LBB0_563
	s_mov_b64 s[8:9], exec
	buffer_inv sc1
	buffer_wbl2 sc1
	s_waitcnt lgkmcnt(0)
	s_waitcnt vmcnt(0)
	v_mbcnt_lo_u32_b32 v1, s8, 0
	v_mbcnt_hi_u32_b32 v1, s9, v1
	v_cmp_eq_u32_e32 vcc, 0, v1
	s_and_saveexec_b64 s[10:11], vcc
	s_cbranch_execz .LBB0_546
	s_bcnt1_i32_b64 s0, s[8:9]
	v_mov_b32_e32 v3, s0
	v_readlane_b32 s0, v255, 4
	v_mov_b32_e32 v2, 0x7000
	v_readlane_b32 s1, v255, 5
	s_nop 4
	global_atomic_add v2, v2, v3, s[0:1] offset:1024 sc0

.LBB0_560:
	s_or_b64 exec, exec, s[8:9]
	s_mov_b64 s[8:9], exec
	v_mbcnt_lo_u32_b32 v0, s8, 0
	v_mbcnt_hi_u32_b32 v0, s9, v0
	v_cmp_eq_u32_e32 vcc, 0, v0
	s_waitcnt vmcnt(0)
	s_and_saveexec_b64 s[10:11], vcc
	s_cbranch_execz .LBB0_562
	s_bcnt1_i32_b64 s0, s[8:9]
	v_mov_b32_e32 v0, 0x2000
	v_mov_b32_e32 v1, s0
	global_atomic_add v0, v1, s[6:7] offset:1024
